# phase-5 scan: the 4 waves fetch a quarter each of the shared P/Q operand tiles and exchange them through LDS (one block barrier per step) instead of each loading all 12 KB per chunk
# speedup vs baseline: 1.0368x; 1.0268x over previous
.LBB0_835:
	v_readfirstlane_b32 s98, v214
	v_and_b32_e32 v234, 63, v218
	v_lshlrev_b32_e32 v234, 4, v234
	v_readlane_b32 s4, v243, 0
	s_lshl_b32 s3, s2, 14
	v_readlane_b32 s10, v243, 6
	v_and_b32_e32 v113, 63, v218
	v_lshl_add_u32 v160, v214, 12, s3
	v_mov_b32_e32 v161, 0
	v_readlane_b32 s6, v243, 2
	v_readlane_b32 s8, v243, 4
	v_readlane_b32 s16, v243, 12
	v_readlane_b32 s17, v243, 13
	v_readlane_b32 s18, v243, 14
	v_readlane_b32 s19, v243, 15
	s_mul_i32 s10, s2, 0xc0000
	v_lshl_add_u64 v[0:1], s[16:17], 0, v[160:161]
	v_lshlrev_b32_e32 v160, 4, v113
	s_lshl_b32 s6, s2, 6
	s_add_i32 s8, s10, 0x63000
	v_readlane_b32 s16, v242, 1
	v_readlane_b32 s5, v243, 1
	v_lshl_add_u64 v[0:1], v[0:1], 0, v[160:161]
	v_lshl_or_b32 v120, v214, 7, v113
	v_readlane_b32 s17, v242, 2
	s_add_u32 s4, s16, s8
	v_readlane_b32 s7, v243, 3
	global_load_dwordx4 v[96:99], v[0:1], off
	global_load_dwordx4 v[100:103], v[0:1], off offset:1024
	global_load_dwordx4 v[104:107], v[0:1], off offset:2048
	global_load_dwordx4 v[108:111], v[0:1], off offset:3072
	v_lshlrev_b32_e32 v0, 6, v113
	s_addc_u32 s5, s17, 0
	v_lshlrev_b32_e32 v160, 3, v120
	v_readlane_b32 s9, v243, 5
	v_readlane_b32 s12, v243, 8
	v_and_b32_e32 v112, 0x3c0, v0
	v_lshrrev_b32_e32 v115, 1, v218
	v_or_b32_e32 v116, 0xc00, v0
	v_lshl_add_u64 v[0:1], s[4:5], 0, v[160:161]
	s_mov_b64 s[0:1], 0x2000
	s_movk_i32 s7, 0x2000
	s_add_u32 s8, s80, s8
	v_and_b32_e32 v114, 24, v115
	v_lshl_or_b32 v118, v214, 8, v113
	v_lshl_add_u64 v[2:3], v[0:1], 0, s[0:1]
	v_add_co_u32_e32 v0, vcc, s7, v0
	s_addc_u32 s9, s81, 0
	s_add_i32 s12, s10, 0x60000
	v_readlane_b32 s11, v243, 7
	v_addc_co_u32_e32 v1, vcc, 0, v1, vcc
	v_lshlrev_b32_e32 v46, 3, v118
	s_add_u32 s10, s16, s12
	v_lshlrev_b32_e32 v32, 1, v114
	v_mov_b32_e32 v33, v161
	s_addc_u32 s11, s17, 0
	global_load_dwordx2 v[162:163], v46, s[4:5] offset:1536
	global_load_dwordx2 v[166:167], v46, s[10:11] offset:512
	global_load_dwordx2 v[170:171], v46, s[10:11]
	global_load_dwordx2 v[164:165], v46, s[4:5] offset:1024
	global_load_dwordx2 v[184:185], v[2:3], off offset:512
	global_load_dwordx2 v[196:197], v[0:1], off
	global_load_dwordx2 v[168:169], v46, s[4:5] offset:512
	global_load_dwordx2 v[172:173], v46, s[4:5]
	v_lshlrev_b32_e32 v34, 1, v112
	v_mov_b32_e32 v35, v161
	v_lshl_add_u64 v[0:1], s[8:9], 0, v[32:33]
	v_lshl_add_u64 v[28:29], v[0:1], 0, v[34:35]
	v_add_co_u32_e32 v4, vcc, s7, v28
	s_movk_i32 s8, 0x1000
	s_nop 0
	v_addc_co_u32_e32 v5, vcc, 0, v29, vcc
	v_add_co_u32_e32 v12, vcc, s8, v28
	s_add_u32 s4, s80, s12
	s_nop 0
	v_addc_co_u32_e32 v13, vcc, 0, v29, vcc
	v_lshl_add_u64 v[38:39], s[10:11], 0, v[160:161]
	s_addc_u32 s5, s81, 0
	v_lshlrev_b32_e32 v36, 1, v116
	v_mov_b32_e32 v37, v161
	v_lshl_add_u64 v[44:45], v[38:39], 0, s[0:1]
	v_add_co_u32_e32 v38, vcc, s7, v38
	v_lshl_add_u64 v[32:33], s[4:5], 0, v[32:33]
	v_lshl_add_u64 v[2:3], v[28:29], 0, s[0:1]
	v_lshl_add_u64 v[0:1], v[0:1], 0, v[36:37]
	v_addc_co_u32_e32 v39, vcc, 0, v39, vcc
	s_waitcnt vmcnt(24)
	v_lshl_add_u64 v[72:73], v[32:33], 0, v[34:35]
	s_cmp_lg_u32 s98, 2
	s_cbranch_scc1 .Lss_g1
	global_load_dwordx4 v[40:43], v[2:3], off offset:2048
.Lss_g1:
	s_cmp_lg_u32 s98, 3
	s_cbranch_scc1 .Lss_g2
	global_load_dwordx4 v[60:63], v[2:3], off offset:64
.Lss_g2:
	s_cmp_lg_u32 s98, 3
	s_cbranch_scc1 .Lss_g3
	global_load_dwordx4 v[48:51], v[2:3], off offset:2112
.Lss_g3:
	s_cmp_lg_u32 s98, 3
	s_cbranch_scc1 .Lss_g4
	global_load_dwordx4 v[76:79], v[4:5], off
.Lss_g4:
	s_nop 0
	s_cmp_lg_u32 s98, 0
	s_cbranch_scc1 .Lss_g5
	global_load_dwordx4 v[4:7], v[0:1], off offset:64
.Lss_g5:
	s_nop 0
	s_cmp_lg_u32 s98, 0
	s_cbranch_scc1 .Lss_g6
	global_load_dwordx4 v[0:3], v[0:1], off
.Lss_g6:
	s_nop 0
	s_cmp_lg_u32 s98, 0
	s_cbranch_scc1 .Lss_g7
	global_load_dwordx4 v[8:11], v[12:13], off offset:64
.Lss_g7:
	s_cmp_lg_u32 s98, 1
	s_cbranch_scc1 .Lss_g8
	global_load_dwordx4 v[20:23], v[12:13], off
.Lss_g8:
	s_nop 0
	s_cmp_lg_u32 s98, 1
	s_cbranch_scc1 .Lss_g9
	global_load_dwordx4 v[12:15], v[28:29], off offset:2112
.Lss_g9:
	s_cmp_lg_u32 s98, 1
	s_cbranch_scc1 .Lss_g10
	global_load_dwordx4 v[16:19], v[28:29], off offset:2048
.Lss_g10:
	s_cmp_lg_u32 s98, 2
	s_cbranch_scc1 .Lss_g11
	global_load_dwordx4 v[24:27], v[28:29], off offset:64
.Lss_g11:
	s_nop 0
	s_cmp_lg_u32 s98, 2
	s_cbranch_scc1 .Lss_g12
	global_load_dwordx4 v[28:31], v[28:29], off
.Lss_g12:
	s_nop 0
	global_load_dwordx2 v[198:199], v[44:45], off offset:512
	global_load_dwordx2 v[200:201], v[38:39], off
	global_load_dwordx2 v[174:175], v46, s[10:11] offset:1536
	global_load_dwordx2 v[178:179], v46, s[10:11] offset:1024
	v_add_co_u32_e32 v38, vcc, s7, v72
	v_lshl_add_u64 v[34:35], v[72:73], 0, s[0:1]
	s_nop 0
	v_addc_co_u32_e32 v39, vcc, 0, v73, vcc
	v_add_co_u32_e32 v52, vcc, s8, v72
	v_lshl_add_u64 v[32:33], v[32:33], 0, v[36:37]
	s_nop 0
	v_addc_co_u32_e32 v53, vcc, 0, v73, vcc
	s_cmp_lg_u32 s98, 2
	s_cbranch_scc1 .Lss_g13
	global_load_dwordx4 v[80:83], v[34:35], off offset:2048
.Lss_g13:
	s_cmp_lg_u32 s98, 3
	s_cbranch_scc1 .Lss_g14
	global_load_dwordx4 v[88:91], v[34:35], off offset:64
.Lss_g14:
	s_cmp_lg_u32 s98, 3
	s_cbranch_scc1 .Lss_g15
	global_load_dwordx4 v[84:87], v[34:35], off offset:2112
.Lss_g15:
	s_cmp_lg_u32 s98, 3
	s_cbranch_scc1 .Lss_g16
	global_load_dwordx4 v[92:95], v[38:39], off
.Lss_g16:
	s_nop 0
	s_cmp_lg_u32 s98, 0
	s_cbranch_scc1 .Lss_g17
	global_load_dwordx4 v[36:39], v[32:33], off offset:64
.Lss_g17:
	s_nop 0
	s_cmp_lg_u32 s98, 0
	s_cbranch_scc1 .Lss_g18
	global_load_dwordx4 v[32:35], v[32:33], off
.Lss_g18:
	s_nop 0
	s_cmp_lg_u32 s98, 0
	s_cbranch_scc1 .Lss_g19
	global_load_dwordx4 v[44:47], v[52:53], off offset:64
.Lss_g19:
	s_cmp_lg_u32 s98, 1
	s_cbranch_scc1 .Lss_g20
	global_load_dwordx4 v[64:67], v[52:53], off
.Lss_g20:
	s_nop 0
	s_cmp_lg_u32 s98, 1
	s_cbranch_scc1 .Lss_g21
	global_load_dwordx4 v[52:55], v[72:73], off offset:2112
.Lss_g21:
	s_cmp_lg_u32 s98, 1
	s_cbranch_scc1 .Lss_g22
	global_load_dwordx4 v[56:59], v[72:73], off offset:2048
.Lss_g22:
	s_cmp_lg_u32 s98, 2
	s_cbranch_scc1 .Lss_g23
	global_load_dwordx4 v[68:71], v[72:73], off offset:64
.Lss_g23:
	s_nop 0
	s_cmp_lg_u32 s98, 2
	s_cbranch_scc1 .Lss_g24
	global_load_dwordx4 v[72:75], v[72:73], off
.Lss_g24:
	v_bfe_u32 v119, v218, 4, 2
	v_mul_u32_u24_e32 v117, 0x1100, v214
	v_mul_u32_u24_e32 v121, 0x110, v119
	v_lshlrev_b32_e32 v113, 2, v113
	s_movk_i32 s9, 0xc0
	v_and_b32_e32 v215, 15, v218
	v_lshlrev_b32_e32 v121, 2, v121
	v_or3_b32 v113, v113, v117, s9
	s_movk_i32 s4, 0x1100
	v_lshl_or_b32 v122, v215, 2, v117
	v_add_u32_e32 v217, v113, v121
	v_mul_u32_u24_e32 v113, 0x110, v215
	v_add_u32_e32 v216, v122, v121
	v_mad_u32_u24 v113, v214, s4, v113
	s_lshl_b32 s4, s2, 8
	v_mov_b32_e32 v121, 0x380f
	v_bitop3_b32 v121, s4, v121, v218 bitop3:0xc8
	s_and_b32 s4, s2, 7
	s_mov_b32 s5, 0
	s_lshl_b32 s4, s4, 7
	v_and_b32_e32 v122, 0x1e0, v115
	v_mov_b32_e32 v123, v161
	v_lshl_add_u64 v[122:123], s[4:5], 0, v[122:123]
	s_lshl_b32 s4, s2, 18
	s_and_b32 s4, s4, 0xe00000
	v_lshlrev_b32_e32 v117, 5, v119
	v_lshlrev_b32_e32 v121, 10, v121
	v_lshl_or_b32 v122, v119, 3, v122
	v_lshl_or_b32 v115, v215, 10, s4
	s_or_b32 s9, s6, 4
	v_or_b32_e32 v160, 0x108000, v121
	v_lshl_add_u64 v[176:177], s[16:17], 0, v[122:123]
	v_or_b32_e32 v180, 0x104000, v121
	v_mov_b32_e32 v181, v161
	v_or_b32_e32 v182, 0x100000, v121
	v_mov_b32_e32 v183, v161
	v_or_b32_e32 v186, 0x110000, v115
	v_mov_b32_e32 v187, v161
	s_mov_b32 s10, 29
	v_lshlrev_b32_e32 v188, 1, v114
	v_mov_b32_e32 v189, v161
	v_lshlrev_b32_e32 v190, 1, v112
	v_mov_b32_e32 v191, v161
	v_lshlrev_b32_e32 v192, 1, v116
	v_mov_b32_e32 v193, v161
	v_lshlrev_b32_e32 v219, 3, v118
	v_lshlrev_b32_e32 v194, 3, v120
	v_mov_b32_e32 v195, v161
	s_mov_b32 s11, 0x3000000
	s_mov_b32 s12, 0x3004000
	s_mov_b64 s[4:5], 0x18000
	v_add_u32_e32 v220, v113, v117
	v_readlane_b32 s13, v243, 9
	v_readlane_b32 s14, v243, 10
	v_readlane_b32 s15, v243, 11
	v_readlane_b32 s18, v242, 3
	v_readlane_b32 s19, v242, 4
	v_readlane_b32 s20, v242, 5
	v_readlane_b32 s21, v242, 6
	v_readlane_b32 s22, v242, 7
	v_readlane_b32 s23, v242, 8
	v_readlane_b32 s24, v242, 9
	v_readlane_b32 s25, v242, 10
	v_readlane_b32 s26, v242, 11
	v_readlane_b32 s27, v242, 12
	v_readlane_b32 s28, v242, 13
	v_readlane_b32 s29, v242, 14
	v_readlane_b32 s30, v242, 15
	v_readlane_b32 s31, v242, 16
	s_waitcnt vmcnt(0)
	s_branch .LBB0_837

.LBB0_837:
	s_mov_b32 s13, s10
	s_add_i32 s14, s13, 5
	s_min_u32 s14, s14, 63
	s_or_b32 s14, s14, s6
	s_add_i32 s10, s10, 3
	s_mul_i32 s16, s14, 0x3000
	s_add_u32 s14, s80, s16
	s_addc_u32 s15, s81, 0
	s_waitcnt vmcnt(63)
	v_lshl_add_u64 v[112:113], s[14:15], 0, v[188:189]
	s_waitcnt vmcnt(63)
	v_lshl_add_u64 v[136:137], v[112:113], 0, v[190:191]
	v_add_co_u32_e32 v114, vcc, s8, v136
	v_readlane_b32 s36, v242, 1
	s_nop 0
	v_addc_co_u32_e32 v115, vcc, 0, v137, vcc
	v_readlane_b32 s37, v242, 2
	s_add_u32 s14, s36, s16
	v_add_co_u32_e32 v138, vcc, s7, v136
	s_addc_u32 s15, s37, 0
	s_nop 0
	v_addc_co_u32_e32 v139, vcc, 0, v137, vcc
	s_waitcnt vmcnt(63)
	v_lshl_add_u64 v[210:211], s[14:15], 0, v[194:195]
	v_lshl_add_u64 v[222:223], v[210:211], 0, s[0:1]
	v_add_co_u32_e32 v210, vcc, s7, v210
	v_lshl_add_u64 v[144:145], v[112:113], 0, v[192:193]
	v_lshl_add_u64 v[146:147], v[136:137], 0, s[0:1]
	v_addc_co_u32_e32 v211, vcc, 0, v211, vcc
	s_cmp_lg_u32 s98, 1
	s_cbranch_scc1 .Lss_g25
	global_load_dwordx4 v[132:135], v[136:137], off
.Lss_g25:
	s_cmp_lg_u32 s98, 1
	s_cbranch_scc1 .Lss_g26
	global_load_dwordx4 v[128:131], v[136:137], off offset:64
.Lss_g26:
	s_cmp_lg_u32 s98, 1
	s_cbranch_scc1 .Lss_g27
	global_load_dwordx4 v[124:127], v[136:137], off offset:2048
.Lss_g27:
	s_cmp_lg_u32 s98, 0
	s_cbranch_scc1 .Lss_g28
	global_load_dwordx4 v[116:119], v[136:137], off offset:2112
.Lss_g28:
	s_cmp_lg_u32 s98, 0
	s_cbranch_scc1 .Lss_g29
	global_load_dwordx4 v[120:123], v[114:115], off offset:64
.Lss_g29:
	s_nop 0
	s_cmp_lg_u32 s98, 0
	s_cbranch_scc1 .Lss_g30
	global_load_dwordx4 v[112:115], v[144:145], off
.Lss_g30:
	s_cmp_lg_u32 s98, 2
	s_cbranch_scc1 .Lss_g31
	global_load_dwordx4 v[140:143], v[138:139], off offset:-4096
.Lss_g31:
	s_cmp_lg_u32 s98, 3
	s_cbranch_scc1 .Lss_g32
	global_load_dwordx4 v[156:159], v[138:139], off
.Lss_g32:
	s_nop 0
	s_cmp_lg_u32 s98, 2
	s_cbranch_scc1 .Lss_g33
	global_load_dwordx4 v[136:139], v[144:145], off offset:64
.Lss_g33:
	s_cmp_lg_u32 s98, 3
	s_cbranch_scc1 .Lss_g34
	global_load_dwordx4 v[152:155], v[146:147], off offset:64
.Lss_g34:
	s_cmp_lg_u32 s98, 3
	s_cbranch_scc1 .Lss_g35
	global_load_dwordx4 v[148:151], v[146:147], off offset:2048
.Lss_g35:
	s_nop 0
	s_cmp_lg_u32 s98, 2
	s_cbranch_scc1 .Lss_g36
	global_load_dwordx4 v[144:147], v[146:147], off offset:2112
.Lss_g36:
	s_nop 0
	global_load_dwordx2 v[208:209], v219, s[14:15]
	global_load_dwordx2 v[206:207], v219, s[14:15] offset:512
	global_load_dwordx2 v[204:205], v219, s[14:15] offset:1024
	global_load_dwordx2 v[202:203], v219, s[14:15] offset:1536
	global_load_dwordx2 v[212:213], v[210:211], off
	s_nop 0
	global_load_dwordx2 v[210:211], v[222:223], off offset:512
	s_waitcnt vmcnt(22)
	s_cmp_lg_u32 s98, 0
	s_cbranch_scc1 .Lss_x61_1
	ds_write_b128 v234, v[32:35] offset:32768
	ds_write_b128 v234, v[36:39] offset:33792
	ds_write_b128 v234, v[44:47] offset:34816
	s_branch .Lss_x61_d
.Lss_x61_1:
	s_cmp_lg_u32 s98, 1
	s_cbranch_scc1 .Lss_x61_2
	ds_write_b128 v234, v[52:55] offset:35840
	ds_write_b128 v234, v[56:59] offset:36864
	ds_write_b128 v234, v[64:67] offset:37888
	s_branch .Lss_x61_d
.Lss_x61_2:
	s_cmp_lg_u32 s98, 2
	s_cbranch_scc1 .Lss_x61_3
	ds_write_b128 v234, v[68:71] offset:38912
	ds_write_b128 v234, v[72:75] offset:39936
	ds_write_b128 v234, v[80:83] offset:40960
	s_branch .Lss_x61_d
.Lss_x61_3:
	ds_write_b128 v234, v[84:87] offset:41984
	ds_write_b128 v234, v[88:91] offset:43008
	ds_write_b128 v234, v[92:95] offset:44032
.Lss_x61_d:
	s_waitcnt lgkmcnt(0)
	s_barrier
	ds_read_b128 v[32:35], v234 offset:32768
	ds_read_b128 v[36:39], v234 offset:33792
	ds_read_b128 v[44:47], v234 offset:34816
	ds_read_b128 v[52:55], v234 offset:35840
	ds_read_b128 v[56:59], v234 offset:36864
	ds_read_b128 v[64:67], v234 offset:37888
	ds_read_b128 v[68:71], v234 offset:38912
	ds_read_b128 v[72:75], v234 offset:39936
	ds_read_b128 v[80:83], v234 offset:40960
	ds_read_b128 v[84:87], v234 offset:41984
	ds_read_b128 v[88:91], v234 offset:43008
	ds_read_b128 v[92:95], v234 offset:44032
	s_waitcnt lgkmcnt(0)
	s_waitcnt vmcnt(63)
	ds_write2_b32 v216, v96, v100 offset1:16
	ds_write2_b32 v216, v98, v102 offset0:136 offset1:152
	s_waitcnt vmcnt(63)
	ds_write2_b32 v216, v104, v97 offset0:32 offset1:68
	ds_write2_b32 v216, v101, v105 offset0:84 offset1:100
	ds_write2_b32 v216, v106, v99 offset0:168 offset1:204
	ds_write2_b32 v216, v103, v107 offset0:220 offset1:236
	s_waitcnt vmcnt(63)
	ds_write2_b32 v217, v108, v109 offset1:68
	ds_write2_b32 v217, v110, v111 offset0:136 offset1:204
	ds_read_b128 v[96:99], v220
	ds_read_b128 v[100:103], v220 offset:16
	ds_read_b128 v[108:111], v220 offset:128
	s_waitcnt vmcnt(63)
	v_lshlrev_b32_e32 v226, 16, v200
	v_and_b32_e32 v227, 0xffff0000, v200
	s_waitcnt lgkmcnt(2)
	v_cvt_pk_bf16_f32 v104, v96, v97
	v_lshlrev_b32_e32 v106, 16, v104
	v_and_b32_e32 v107, 0xffff0000, v104
	v_cvt_pk_bf16_f32 v105, v98, v99
	v_pk_add_f32 v[96:97], v[96:97], v[106:107] neg_lo:[0,1] neg_hi:[0,1]
	v_lshlrev_b32_e32 v106, 16, v105
	v_and_b32_e32 v107, 0xffff0000, v105
	v_pk_add_f32 v[98:99], v[98:99], v[106:107] neg_lo:[0,1] neg_hi:[0,1]
	s_waitcnt lgkmcnt(1)
	v_cvt_pk_bf16_f32 v106, v100, v101
	v_cvt_pk_bf16_f32 v96, v96, v97
	v_cvt_pk_bf16_f32 v97, v98, v99
	v_lshlrev_b32_e32 v98, 16, v106
	v_and_b32_e32 v99, 0xffff0000, v106
	v_cvt_pk_bf16_f32 v107, v102, v103
	v_pk_add_f32 v[98:99], v[100:101], v[98:99] neg_lo:[0,1] neg_hi:[0,1]
	v_lshlrev_b32_e32 v100, 16, v107
	v_and_b32_e32 v101, 0xffff0000, v107
	v_pk_add_f32 v[100:101], v[102:103], v[100:101] neg_lo:[0,1] neg_hi:[0,1]
	v_cvt_pk_bf16_f32 v98, v98, v99
	v_cvt_pk_bf16_f32 v99, v100, v101
	ds_read_b128 v[100:103], v220 offset:144
	s_waitcnt lgkmcnt(1)
	v_cvt_pk_bf16_f32 v222, v108, v109
	v_lshlrev_b32_e32 v228, 16, v201
	v_and_b32_e32 v229, 0xffff0000, v201
	v_lshlrev_b32_e32 v224, 16, v222
	v_and_b32_e32 v225, 0xffff0000, v222
	v_cvt_pk_bf16_f32 v223, v110, v111
	s_waitcnt vmcnt(63)
	v_mfma_f32_16x16x32_bf16 v[226:229], v[104:107], v[92:95], v[226:229]
	v_add_f32_e64 v108, v108, -v224
	v_add_f32_e64 v109, v109, -v225
	v_lshlrev_b32_e32 v224, 16, v223
	v_and_b32_e32 v225, 0xffff0000, v223
	v_pk_add_f32 v[110:111], v[110:111], v[224:225] neg_lo:[0,1] neg_hi:[0,1]
	s_waitcnt lgkmcnt(0)
	v_cvt_pk_bf16_f32 v224, v100, v101
	v_cvt_pk_bf16_f32 v108, v108, v109
	v_cvt_pk_bf16_f32 v109, v110, v111
	v_lshlrev_b32_e32 v110, 16, v224
	v_and_b32_e32 v111, 0xffff0000, v224
	v_cvt_pk_bf16_f32 v225, v102, v103
	v_pk_add_f32 v[100:101], v[100:101], v[110:111] neg_lo:[0,1] neg_hi:[0,1]
	v_mfma_f32_16x16x32_bf16 v[92:95], v[96:99], v[92:95], v[226:229]
	v_cvt_pk_bf16_f32 v110, v100, v101
	v_lshlrev_b32_e32 v100, 16, v225
	v_and_b32_e32 v101, 0xffff0000, v225
	v_pk_add_f32 v[100:101], v[102:103], v[100:101] neg_lo:[0,1] neg_hi:[0,1]
	v_mfma_f32_16x16x32_bf16 v[92:95], v[222:225], v[88:91], v[92:95]
	v_cvt_pk_bf16_f32 v111, v100, v101
	s_add_i32 s13, s13, 6
	s_min_u32 s13, s13, 63
	v_mfma_f32_16x16x32_bf16 v[88:91], v[108:111], v[88:91], v[92:95]
	s_or_b32 s13, s13, s6
	s_nop 2
	v_lshlrev_b32_e32 v92, 16, v198
	v_and_b32_e32 v93, 0xffff0000, v198
	v_lshlrev_b32_e32 v94, 16, v199
	v_and_b32_e32 v95, 0xffff0000, v199
	s_mulk_i32 s13, 0x3000
	s_add_u32 s14, s80, s13
	v_mfma_f32_16x16x32_bf16 v[92:95], v[104:107], v[80:83], v[92:95]
	s_addc_u32 s15, s81, 0
	v_readlane_b32 s38, v242, 3
	v_readlane_b32 s39, v242, 4
	v_mfma_f32_16x16x32_bf16 v[80:83], v[96:99], v[80:83], v[92:95]
	v_readlane_b32 s40, v242, 5
	v_readlane_b32 s41, v242, 6
	v_readlane_b32 s42, v242, 7
	v_mfma_f32_16x16x32_bf16 v[80:83], v[222:225], v[84:87], v[80:83]
	v_readlane_b32 s43, v242, 8
	v_readlane_b32 s44, v242, 9
	v_readlane_b32 s45, v242, 10
	v_mfma_f32_16x16x32_bf16 v[80:83], v[108:111], v[84:87], v[80:83]
	v_lshlrev_b32_e32 v84, 16, v170
	v_and_b32_e32 v85, 0xffff0000, v170
	v_lshlrev_b32_e32 v86, 16, v171
	v_and_b32_e32 v87, 0xffff0000, v171
	v_readlane_b32 s46, v242, 11
	v_readlane_b32 s47, v242, 12
	s_waitcnt vmcnt(63)
	v_mfma_f32_16x16x32_bf16 v[84:87], v[104:107], v[72:75], v[84:87]
	v_readlane_b32 s48, v242, 13
	v_readlane_b32 s49, v242, 14
	v_readlane_b32 s50, v242, 15
	v_mfma_f32_16x16x32_bf16 v[72:75], v[96:99], v[72:75], v[84:87]
	v_readlane_b32 s51, v242, 16
	v_mfma_f32_16x16x32_bf16 v[72:75], v[222:225], v[68:71], v[72:75]
	v_mfma_f32_16x16x32_bf16 v[100:103], v[108:111], v[68:71], v[72:75]
	v_lshlrev_b32_e32 v68, 16, v166
	v_and_b32_e32 v69, 0xffff0000, v166
	v_lshlrev_b32_e32 v70, 16, v167
	v_and_b32_e32 v71, 0xffff0000, v167
	s_nop 1
	v_mfma_f32_16x16x32_bf16 v[68:71], v[104:107], v[56:59], v[68:71]
	v_mfma_f32_16x16x32_bf16 v[56:59], v[96:99], v[56:59], v[68:71]
	v_mfma_f32_16x16x32_bf16 v[56:59], v[222:225], v[52:55], v[56:59]
	v_mfma_f32_16x16x32_bf16 v[226:229], v[108:111], v[52:55], v[56:59]
	v_lshlrev_b32_e32 v52, 16, v178
	v_and_b32_e32 v53, 0xffff0000, v178
	v_lshlrev_b32_e32 v54, 16, v179
	v_and_b32_e32 v55, 0xffff0000, v179
	s_nop 1
	v_mfma_f32_16x16x32_bf16 v[52:55], v[104:107], v[64:67], v[52:55]
	v_mfma_f32_16x16x32_bf16 v[52:55], v[96:99], v[64:67], v[52:55]
	v_mfma_f32_16x16x32_bf16 v[52:55], v[222:225], v[44:47], v[52:55]
	v_mfma_f32_16x16x32_bf16 v[230:233], v[108:111], v[44:47], v[52:55]
	v_lshlrev_b32_e32 v44, 16, v174
	v_and_b32_e32 v45, 0xffff0000, v174
	v_lshlrev_b32_e32 v46, 16, v175
	v_and_b32_e32 v47, 0xffff0000, v175
	s_nop 1
	v_mfma_f32_16x16x32_bf16 v[44:47], v[104:107], v[32:35], v[44:47]
	v_mfma_f32_16x16x32_bf16 v[32:35], v[96:99], v[32:35], v[44:47]
	v_mfma_f32_16x16x32_bf16 v[32:35], v[222:225], v[36:39], v[32:35]
	v_mfma_f32_16x16x32_bf16 v[96:99], v[108:111], v[36:39], v[32:35]
	s_nop 6
	v_lshl_add_u64 v[34:35], v[176:177], 0, v[182:183]
	v_add_co_u32_e32 v34, vcc, s11, v34
	v_cvt_pk_bf16_f32 v32, v88, v89
	v_cvt_pk_bf16_f32 v33, v90, v91
	v_addc_co_u32_e32 v35, vcc, 0, v35, vcc
	global_store_dwordx2 v[34:35], v[32:33], off
	v_lshl_add_u64 v[34:35], v[176:177], 0, v[180:181]
	v_add_co_u32_e32 v34, vcc, s11, v34
	v_cvt_pk_bf16_f32 v32, v80, v81
	v_cvt_pk_bf16_f32 v33, v82, v83
	v_addc_co_u32_e32 v35, vcc, 0, v35, vcc
	global_store_dwordx2 v[34:35], v[32:33], off
	v_lshl_add_u64 v[32:33], s[14:15], 0, v[188:189]
	v_lshl_add_u64 v[36:37], v[32:33], 0, v[190:191]
	v_add_co_u32_e32 v34, vcc, s8, v36
	s_add_u32 s14, s36, s13
	s_nop 0
	v_addc_co_u32_e32 v35, vcc, 0, v37, vcc
	v_add_co_u32_e32 v38, vcc, s7, v36
	s_addc_u32 s15, s37, 0
	s_nop 0
	v_addc_co_u32_e32 v39, vcc, 0, v37, vcc
	v_lshl_add_u64 v[104:105], s[14:15], 0, v[194:195]
	v_lshl_add_u64 v[106:107], v[104:105], 0, s[0:1]
	v_add_co_u32_e32 v104, vcc, s7, v104
	v_lshl_add_u64 v[80:81], v[32:33], 0, v[192:193]
	v_lshl_add_u64 v[84:85], v[36:37], 0, s[0:1]
	v_addc_co_u32_e32 v105, vcc, 0, v105, vcc
	s_cmp_lg_u32 s98, 2
	s_cbranch_scc1 .Lss_g37
	global_load_dwordx4 v[72:75], v[36:37], off
.Lss_g37:
	s_cmp_lg_u32 s98, 2
	s_cbranch_scc1 .Lss_g38
	global_load_dwordx4 v[68:71], v[36:37], off offset:64
.Lss_g38:
	s_cmp_lg_u32 s98, 1
	s_cbranch_scc1 .Lss_g39
	global_load_dwordx4 v[56:59], v[36:37], off offset:2048
.Lss_g39:
	s_cmp_lg_u32 s98, 1
	s_cbranch_scc1 .Lss_g40
	global_load_dwordx4 v[52:55], v[36:37], off offset:2112
.Lss_g40:
	s_cmp_lg_u32 s98, 0
	s_cbranch_scc1 .Lss_g41
	global_load_dwordx4 v[44:47], v[34:35], off offset:64
.Lss_g41:
	s_nop 0
	s_cmp_lg_u32 s98, 0
	s_cbranch_scc1 .Lss_g42
	global_load_dwordx4 v[32:35], v[80:81], off
.Lss_g42:
	s_cmp_lg_u32 s98, 1
	s_cbranch_scc1 .Lss_g43
	global_load_dwordx4 v[64:67], v[38:39], off offset:-4096

.Lss_g44:
	s_nop 0
	s_cmp_lg_u32 s98, 0
	s_cbranch_scc1 .Lss_g45
	global_load_dwordx4 v[36:39], v[80:81], off offset:64
.Lss_g45:
	s_cmp_lg_u32 s98, 3
	s_cbranch_scc1 .Lss_g46
	global_load_dwordx4 v[88:91], v[84:85], off offset:64
.Lss_g46:
	s_nop 0
	s_cmp_lg_u32 s98, 2
	s_cbranch_scc1 .Lss_g47
	global_load_dwordx4 v[80:83], v[84:85], off offset:2048
.Lss_g47:
	s_nop 0
	s_cmp_lg_u32 s98, 3
	s_cbranch_scc1 .Lss_g48
	global_load_dwordx4 v[84:87], v[84:85], off offset:2112
.Lss_g48:
	s_nop 0
	global_load_dwordx2 v[170:171], v219, s[14:15]
	global_load_dwordx2 v[166:167], v219, s[14:15] offset:512
	global_load_dwordx2 v[178:179], v219, s[14:15] offset:1024
	global_load_dwordx2 v[174:175], v219, s[14:15] offset:1536
	global_load_dwordx2 v[200:201], v[104:105], off
	global_load_dwordx2 v[198:199], v[106:107], off offset:512
	s_waitcnt vmcnt(22)
	s_cmp_lg_u32 s98, 0
	s_cbranch_scc1 .Lss_x62_1
	ds_write_b128 v234, v[0:3] offset:45056
	ds_write_b128 v234, v[4:7] offset:46080
	ds_write_b128 v234, v[8:11] offset:47104
	s_branch .Lss_x62_d
.Lss_x62_1:
	s_cmp_lg_u32 s98, 1
	s_cbranch_scc1 .Lss_x62_2
	ds_write_b128 v234, v[12:15] offset:48128
	ds_write_b128 v234, v[16:19] offset:49152
	ds_write_b128 v234, v[20:23] offset:50176
	s_branch .Lss_x62_d
.Lss_x62_2:
	s_cmp_lg_u32 s98, 2
	s_cbranch_scc1 .Lss_x62_3
	ds_write_b128 v234, v[24:27] offset:51200
	ds_write_b128 v234, v[28:31] offset:52224
	ds_write_b128 v234, v[40:43] offset:53248
	s_branch .Lss_x62_d
.Lss_x62_3:
	ds_write_b128 v234, v[48:51] offset:54272
	ds_write_b128 v234, v[60:63] offset:55296
	ds_write_b128 v234, v[76:79] offset:56320
.Lss_x62_d:
	s_waitcnt lgkmcnt(0)
	s_barrier
	ds_read_b128 v[0:3], v234 offset:45056
	ds_read_b128 v[4:7], v234 offset:46080
	ds_read_b128 v[8:11], v234 offset:47104
	ds_read_b128 v[12:15], v234 offset:48128
	ds_read_b128 v[16:19], v234 offset:49152
	ds_read_b128 v[20:23], v234 offset:50176
	ds_read_b128 v[24:27], v234 offset:51200
	ds_read_b128 v[28:31], v234 offset:52224
	ds_read_b128 v[40:43], v234 offset:53248
	ds_read_b128 v[48:51], v234 offset:54272
	ds_read_b128 v[60:63], v234 offset:55296
	ds_read_b128 v[76:79], v234 offset:56320
	s_waitcnt lgkmcnt(0)
	ds_write2_b32 v216, v100, v226 offset1:16
	ds_write2_b32 v216, v102, v228 offset0:136 offset1:152
	ds_write2_b32 v216, v230, v101 offset0:32 offset1:68
	ds_write2_b32 v216, v227, v231 offset0:84 offset1:100
	ds_write2_b32 v216, v232, v103 offset0:168 offset1:204
	ds_write2_b32 v216, v229, v233 offset0:220 offset1:236
	ds_write2_b32 v217, v96, v97 offset1:68
	ds_write2_b32 v217, v98, v99 offset0:136 offset1:204
	ds_read_b128 v[96:99], v220
	ds_read_b128 v[100:103], v220 offset:16
	s_min_u32 s13, s10, 59
	s_add_i32 s13, s9, s13
	s_mulk_i32 s13, 0x3000
	s_waitcnt lgkmcnt(1)
	v_cvt_pk_bf16_f32 v108, v96, v97
	v_lshlrev_b32_e32 v104, 16, v108
	v_and_b32_e32 v105, 0xffff0000, v108
	v_pk_add_f32 v[96:97], v[96:97], v[104:105] neg_lo:[0,1] neg_hi:[0,1]
	v_cvt_pk_bf16_f32 v109, v98, v99
	v_cvt_pk_bf16_f32 v222, v96, v97
	v_lshlrev_b32_e32 v96, 16, v109
	v_and_b32_e32 v97, 0xffff0000, v109
	v_pk_add_f32 v[96:97], v[98:99], v[96:97] neg_lo:[0,1] neg_hi:[0,1]
	s_waitcnt lgkmcnt(0)
	v_cvt_pk_bf16_f32 v110, v100, v101
	v_cvt_pk_bf16_f32 v223, v96, v97
	v_lshlrev_b32_e32 v96, 16, v110
	v_and_b32_e32 v97, 0xffff0000, v110
	v_pk_add_f32 v[96:97], v[100:101], v[96:97] neg_lo:[0,1] neg_hi:[0,1]
	v_cvt_pk_bf16_f32 v111, v102, v103
	v_cvt_pk_bf16_f32 v224, v96, v97
	ds_read_b128 v[96:99], v220 offset:128
	v_lshlrev_b32_e32 v100, 16, v111
	v_and_b32_e32 v101, 0xffff0000, v111
	v_pk_add_f32 v[100:101], v[102:103], v[100:101] neg_lo:[0,1] neg_hi:[0,1]
	s_add_u32 s14, s80, s13
	v_cvt_pk_bf16_f32 v225, v100, v101
	ds_read_b128 v[100:103], v220 offset:144
	s_waitcnt lgkmcnt(1)
	v_cvt_pk_bf16_f32 v226, v96, v97
	v_lshlrev_b32_e32 v104, 16, v226
	v_and_b32_e32 v105, 0xffff0000, v226
	v_pk_add_f32 v[96:97], v[96:97], v[104:105] neg_lo:[0,1] neg_hi:[0,1]
	v_cvt_pk_bf16_f32 v227, v98, v99
	v_cvt_pk_bf16_f32 v230, v96, v97
	v_lshlrev_b32_e32 v96, 16, v227
	v_and_b32_e32 v97, 0xffff0000, v227
	v_pk_add_f32 v[96:97], v[98:99], v[96:97] neg_lo:[0,1] neg_hi:[0,1]
	v_lshlrev_b32_e32 v98, 16, v197
	v_cvt_pk_bf16_f32 v231, v96, v97
	v_lshlrev_b32_e32 v96, 16, v196
	v_and_b32_e32 v97, 0xffff0000, v196
	v_and_b32_e32 v99, 0xffff0000, v197
	s_waitcnt lgkmcnt(0)
	v_cvt_pk_bf16_f32 v228, v100, v101
	v_cvt_pk_bf16_f32 v229, v102, v103
	v_mfma_f32_16x16x32_bf16 v[96:99], v[108:111], v[76:79], v[96:99]
	v_lshlrev_b32_e32 v104, 16, v228
	v_and_b32_e32 v105, 0xffff0000, v228
	v_pk_add_f32 v[100:101], v[100:101], v[104:105] neg_lo:[0,1] neg_hi:[0,1]
	v_mfma_f32_16x16x32_bf16 v[76:79], v[222:225], v[76:79], v[96:99]
	v_cvt_pk_bf16_f32 v232, v100, v101
	s_addc_u32 s15, s81, 0
	s_nop 1
	v_lshlrev_b32_e32 v96, 16, v229
	v_and_b32_e32 v97, 0xffff0000, v229
	v_pk_add_f32 v[96:97], v[102:103], v[96:97] neg_lo:[0,1] neg_hi:[0,1]
	v_mfma_f32_16x16x32_bf16 v[76:79], v[226:229], v[60:63], v[76:79]
	v_cvt_pk_bf16_f32 v233, v96, v97
	s_nop 1
	v_mfma_f32_16x16x32_bf16 v[60:63], v[230:233], v[60:63], v[76:79]
	s_nop 3
	v_lshlrev_b32_e32 v76, 16, v184
	v_and_b32_e32 v77, 0xffff0000, v184
	v_lshlrev_b32_e32 v78, 16, v185
	v_and_b32_e32 v79, 0xffff0000, v185
	s_nop 1
	v_mfma_f32_16x16x32_bf16 v[76:79], v[108:111], v[40:43], v[76:79]
	v_mfma_f32_16x16x32_bf16 v[40:43], v[222:225], v[40:43], v[76:79]
	v_mfma_f32_16x16x32_bf16 v[40:43], v[226:229], v[48:51], v[40:43]
	v_mfma_f32_16x16x32_bf16 v[40:43], v[230:233], v[48:51], v[40:43]
	v_lshlrev_b32_e32 v48, 16, v172
	v_and_b32_e32 v49, 0xffff0000, v172
	v_lshlrev_b32_e32 v50, 16, v173
	v_and_b32_e32 v51, 0xffff0000, v173
	s_nop 1
	v_mfma_f32_16x16x32_bf16 v[48:51], v[108:111], v[28:31], v[48:51]
	v_mfma_f32_16x16x32_bf16 v[28:31], v[222:225], v[28:31], v[48:51]
	v_mfma_f32_16x16x32_bf16 v[28:31], v[226:229], v[24:27], v[28:31]
	v_mfma_f32_16x16x32_bf16 v[96:99], v[230:233], v[24:27], v[28:31]
	v_lshlrev_b32_e32 v24, 16, v168
	v_and_b32_e32 v25, 0xffff0000, v168
	v_lshlrev_b32_e32 v26, 16, v169
	v_and_b32_e32 v27, 0xffff0000, v169
	s_nop 1
	v_mfma_f32_16x16x32_bf16 v[24:27], v[108:111], v[16:19], v[24:27]
	v_mfma_f32_16x16x32_bf16 v[16:19], v[222:225], v[16:19], v[24:27]
	v_mfma_f32_16x16x32_bf16 v[16:19], v[226:229], v[12:15], v[16:19]
	v_mfma_f32_16x16x32_bf16 v[100:103], v[230:233], v[12:15], v[16:19]
	v_lshlrev_b32_e32 v12, 16, v164
	v_and_b32_e32 v13, 0xffff0000, v164
	v_lshlrev_b32_e32 v14, 16, v165
	v_and_b32_e32 v15, 0xffff0000, v165
	s_nop 1
	v_mfma_f32_16x16x32_bf16 v[12:15], v[108:111], v[20:23], v[12:15]
	v_mfma_f32_16x16x32_bf16 v[12:15], v[222:225], v[20:23], v[12:15]
	v_mfma_f32_16x16x32_bf16 v[12:15], v[226:229], v[8:11], v[12:15]
	v_mfma_f32_16x16x32_bf16 v[104:107], v[230:233], v[8:11], v[12:15]
	v_lshlrev_b32_e32 v8, 16, v162
	v_and_b32_e32 v9, 0xffff0000, v162
	v_lshlrev_b32_e32 v10, 16, v163
	v_and_b32_e32 v11, 0xffff0000, v163
	s_nop 1
	v_mfma_f32_16x16x32_bf16 v[8:11], v[108:111], v[0:3], v[8:11]
	v_mfma_f32_16x16x32_bf16 v[0:3], v[222:225], v[0:3], v[8:11]
	v_mfma_f32_16x16x32_bf16 v[0:3], v[226:229], v[4:7], v[0:3]
	v_mfma_f32_16x16x32_bf16 v[108:111], v[230:233], v[4:7], v[0:3]
	s_nop 6
	v_lshl_add_u64 v[2:3], v[176:177], 0, v[160:161]
	v_add_co_u32_e32 v4, vcc, s11, v2
	v_cvt_pk_bf16_f32 v0, v60, v61
	s_nop 0
	v_addc_co_u32_e32 v5, vcc, 0, v3, vcc
	v_cvt_pk_bf16_f32 v1, v62, v63
	v_add_co_u32_e32 v2, vcc, s12, v2
	global_store_dwordx2 v[4:5], v[0:1], off
	v_cvt_pk_bf16_f32 v0, v40, v41
	v_cvt_pk_bf16_f32 v1, v42, v43
	v_addc_co_u32_e32 v3, vcc, 0, v3, vcc
	global_store_dwordx2 v[2:3], v[0:1], off
	v_lshl_add_u64 v[0:1], s[14:15], 0, v[188:189]
	v_lshl_add_u64 v[4:5], v[0:1], 0, v[190:191]
	v_add_co_u32_e32 v2, vcc, s8, v4
	v_lshl_add_u64 v[40:41], v[0:1], 0, v[192:193]
	s_nop 0
	v_addc_co_u32_e32 v3, vcc, 0, v5, vcc
	v_add_co_u32_e32 v6, vcc, s7, v4
	s_add_u32 s14, s36, s13
	s_addc_u32 s15, s37, 0
	s_nop 0
	v_addc_co_u32_e32 v7, vcc, 0, v5, vcc
	v_lshl_add_u64 v[48:49], v[4:5], 0, s[0:1]
	s_cmp_lg_u32 s98, 2
	s_cbranch_scc1 .Lss_g49
	global_load_dwordx4 v[28:31], v[4:5], off
.Lss_g49:
	s_cmp_lg_u32 s98, 2
	s_cbranch_scc1 .Lss_g50
	global_load_dwordx4 v[24:27], v[4:5], off offset:64
.Lss_g50:
	s_cmp_lg_u32 s98, 1
	s_cbranch_scc1 .Lss_g51
	global_load_dwordx4 v[16:19], v[4:5], off offset:2048
.Lss_g51:
	s_cmp_lg_u32 s98, 1
	s_cbranch_scc1 .Lss_g52
	global_load_dwordx4 v[12:15], v[4:5], off offset:2112
.Lss_g52:
	s_cmp_lg_u32 s98, 0
	s_cbranch_scc1 .Lss_g53
	global_load_dwordx4 v[8:11], v[2:3], off offset:64
.Lss_g53:
	s_nop 0
	s_cmp_lg_u32 s98, 0
	s_cbranch_scc1 .Lss_g54
	global_load_dwordx4 v[0:3], v[40:41], off
.Lss_g54:
	s_cmp_lg_u32 s98, 1
	s_cbranch_scc1 .Lss_g55
	global_load_dwordx4 v[20:23], v[6:7], off offset:-4096
.Lss_g55:
	s_cmp_lg_u32 s98, 3
	s_cbranch_scc1 .Lss_g56
	global_load_dwordx4 v[76:79], v[6:7], off
.Lss_g56:
	s_nop 0
	s_cmp_lg_u32 s98, 0
	s_cbranch_scc1 .Lss_g57
	global_load_dwordx4 v[4:7], v[40:41], off offset:64
.Lss_g57:
	s_cmp_lg_u32 s98, 3
	s_cbranch_scc1 .Lss_g58
	global_load_dwordx4 v[60:63], v[48:49], off offset:64
.Lss_g58:
	s_nop 0
	s_cmp_lg_u32 s98, 2
	s_cbranch_scc1 .Lss_g59
	global_load_dwordx4 v[40:43], v[48:49], off offset:2048
.Lss_g59:
	s_nop 0
	s_cmp_lg_u32 s98, 3
	s_cbranch_scc1 .Lss_g60
	global_load_dwordx4 v[48:51], v[48:49], off offset:2112
.Lss_g60:
	s_nop 0
	global_load_dwordx2 v[172:173], v219, s[14:15]
	global_load_dwordx2 v[168:169], v219, s[14:15] offset:512
	global_load_dwordx2 v[164:165], v219, s[14:15] offset:1024
	global_load_dwordx2 v[162:163], v219, s[14:15] offset:1536
	v_lshl_add_u64 v[184:185], s[14:15], 0, v[194:195]
	v_lshl_add_u64 v[222:223], v[184:185], 0, s[0:1]
	v_add_co_u32_e32 v184, vcc, 0x2000, v184
	s_cmp_gt_u32 s10, 61
	s_nop 0
	v_addc_co_u32_e32 v185, vcc, 0, v185, vcc
	global_load_dwordx2 v[196:197], v[184:185], off
	s_nop 0
	global_load_dwordx2 v[184:185], v[222:223], off offset:512
	s_cbranch_scc1 .LBB0_836
	s_waitcnt vmcnt(22)
	s_cmp_lg_u32 s98, 0
	s_cbranch_scc1 .Lss_x63_1
	ds_write_b128 v234, v[112:115] offset:20480
	ds_write_b128 v234, v[116:119] offset:21504
	ds_write_b128 v234, v[120:123] offset:22528
	s_branch .Lss_x63_d
.Lss_x63_1:
	s_cmp_lg_u32 s98, 1
	s_cbranch_scc1 .Lss_x63_2
	ds_write_b128 v234, v[124:127] offset:23552
	ds_write_b128 v234, v[128:131] offset:24576
	ds_write_b128 v234, v[132:135] offset:25600
	s_branch .Lss_x63_d
.Lss_x63_2:
	s_cmp_lg_u32 s98, 2
	s_cbranch_scc1 .Lss_x63_3
	ds_write_b128 v234, v[136:139] offset:26624
	ds_write_b128 v234, v[140:143] offset:27648
	ds_write_b128 v234, v[144:147] offset:28672
	s_branch .Lss_x63_d
.Lss_x63_3:
	ds_write_b128 v234, v[148:151] offset:29696
	ds_write_b128 v234, v[152:155] offset:30720
	ds_write_b128 v234, v[156:159] offset:31744
.Lss_x63_d:
	s_waitcnt lgkmcnt(0)
	s_barrier
	ds_read_b128 v[112:115], v234 offset:20480
	ds_read_b128 v[116:119], v234 offset:21504
	ds_read_b128 v[120:123], v234 offset:22528
	ds_read_b128 v[124:127], v234 offset:23552
	ds_read_b128 v[128:131], v234 offset:24576
	ds_read_b128 v[132:135], v234 offset:25600
	ds_read_b128 v[136:139], v234 offset:26624
	ds_read_b128 v[140:143], v234 offset:27648
	ds_read_b128 v[144:147], v234 offset:28672
	ds_read_b128 v[148:151], v234 offset:29696
	ds_read_b128 v[152:155], v234 offset:30720
	ds_read_b128 v[156:159], v234 offset:31744
	s_waitcnt lgkmcnt(0)
	ds_write2_b32 v216, v96, v100 offset1:16
	ds_write2_b32 v216, v98, v102 offset0:136 offset1:152
	ds_write2_b32 v216, v104, v97 offset0:32 offset1:68
	ds_write2_b32 v216, v101, v105 offset0:84 offset1:100
	ds_write2_b32 v216, v106, v99 offset0:168 offset1:204
	ds_write2_b32 v216, v103, v107 offset0:220 offset1:236
	ds_write2_b32 v217, v108, v109 offset1:68
	ds_write2_b32 v217, v110, v111 offset0:136 offset1:204
	ds_read_b128 v[96:99], v220
	ds_read_b128 v[100:103], v220 offset:16
	s_waitcnt vmcnt(63)
	v_lshlrev_b32_e32 v106, 16, v205
	v_and_b32_e32 v107, 0xffff0000, v205
	s_waitcnt lgkmcnt(1)
	v_cvt_pk_bf16_f32 v108, v96, v97
	v_lshlrev_b32_e32 v104, 16, v108
	v_and_b32_e32 v105, 0xffff0000, v108
	v_pk_add_f32 v[96:97], v[96:97], v[104:105] neg_lo:[0,1] neg_hi:[0,1]
	v_cvt_pk_bf16_f32 v109, v98, v99
	v_cvt_pk_bf16_f32 v222, v96, v97
	v_lshlrev_b32_e32 v96, 16, v109
	v_and_b32_e32 v97, 0xffff0000, v109
	v_pk_add_f32 v[96:97], v[98:99], v[96:97] neg_lo:[0,1] neg_hi:[0,1]
	s_waitcnt lgkmcnt(0)
	v_cvt_pk_bf16_f32 v110, v100, v101
	v_cvt_pk_bf16_f32 v223, v96, v97
	v_lshlrev_b32_e32 v96, 16, v110
	v_and_b32_e32 v97, 0xffff0000, v110
	v_pk_add_f32 v[96:97], v[100:101], v[96:97] neg_lo:[0,1] neg_hi:[0,1]
	v_cvt_pk_bf16_f32 v111, v102, v103
	v_cvt_pk_bf16_f32 v224, v96, v97
	ds_read_b128 v[96:99], v220 offset:128
	v_lshlrev_b32_e32 v100, 16, v111
	v_and_b32_e32 v101, 0xffff0000, v111
	v_pk_add_f32 v[100:101], v[102:103], v[100:101] neg_lo:[0,1] neg_hi:[0,1]
	s_nop 0
	v_cvt_pk_bf16_f32 v225, v100, v101
	ds_read_b128 v[100:103], v220 offset:144
	s_waitcnt lgkmcnt(1)
	v_cvt_pk_bf16_f32 v226, v96, v97
	v_lshlrev_b32_e32 v104, 16, v226
	v_and_b32_e32 v105, 0xffff0000, v226
	v_pk_add_f32 v[96:97], v[96:97], v[104:105] neg_lo:[0,1] neg_hi:[0,1]
	v_cvt_pk_bf16_f32 v227, v98, v99
	v_cvt_pk_bf16_f32 v230, v96, v97
	v_lshlrev_b32_e32 v96, 16, v227
	v_and_b32_e32 v97, 0xffff0000, v227
	v_pk_add_f32 v[96:97], v[98:99], v[96:97] neg_lo:[0,1] neg_hi:[0,1]
	s_waitcnt vmcnt(63)
	v_lshlrev_b32_e32 v98, 16, v213
	v_cvt_pk_bf16_f32 v231, v96, v97
	v_lshlrev_b32_e32 v96, 16, v212
	v_and_b32_e32 v97, 0xffff0000, v212
	v_and_b32_e32 v99, 0xffff0000, v213
	s_waitcnt lgkmcnt(0)
	v_cvt_pk_bf16_f32 v228, v100, v101
	v_lshlrev_b32_e32 v104, 16, v228
	v_mfma_f32_16x16x32_bf16 v[96:99], v[108:111], v[156:159], v[96:99]
	v_and_b32_e32 v105, 0xffff0000, v228
	v_cvt_pk_bf16_f32 v229, v102, v103
	v_pk_add_f32 v[100:101], v[100:101], v[104:105] neg_lo:[0,1] neg_hi:[0,1]
	v_mfma_f32_16x16x32_bf16 v[96:99], v[222:225], v[156:159], v[96:99]
	v_cvt_pk_bf16_f32 v232, v100, v101
	v_lshlrev_b32_e32 v100, 16, v229
	v_and_b32_e32 v101, 0xffff0000, v229
	v_pk_add_f32 v[100:101], v[102:103], v[100:101] neg_lo:[0,1] neg_hi:[0,1]
	v_mfma_f32_16x16x32_bf16 v[96:99], v[226:229], v[152:155], v[96:99]
	v_cvt_pk_bf16_f32 v233, v100, v101
	v_lshlrev_b32_e32 v100, 16, v206
	v_and_b32_e32 v101, 0xffff0000, v206
	v_mfma_f32_16x16x32_bf16 v[152:155], v[230:233], v[152:155], v[96:99]
	v_lshlrev_b32_e32 v102, 16, v207
	s_waitcnt vmcnt(63)
	s_nop 1
	v_lshlrev_b32_e32 v96, 16, v210
	v_and_b32_e32 v97, 0xffff0000, v210
	v_lshlrev_b32_e32 v98, 16, v211
	v_and_b32_e32 v99, 0xffff0000, v211
	v_and_b32_e32 v103, 0xffff0000, v207
	v_lshlrev_b32_e32 v104, 16, v204
	v_mfma_f32_16x16x32_bf16 v[96:99], v[108:111], v[148:151], v[96:99]
	v_and_b32_e32 v105, 0xffff0000, v204
	v_mfma_f32_16x16x32_bf16 v[100:103], v[108:111], v[124:127], v[100:103]
	v_mfma_f32_16x16x32_bf16 v[96:99], v[222:225], v[148:151], v[96:99]
	v_mfma_f32_16x16x32_bf16 v[100:103], v[222:225], v[124:127], v[100:103]
	v_mfma_f32_16x16x32_bf16 v[96:99], v[226:229], v[144:147], v[96:99]
	v_mfma_f32_16x16x32_bf16 v[100:103], v[226:229], v[116:119], v[100:103]
	v_mfma_f32_16x16x32_bf16 v[144:147], v[230:233], v[144:147], v[96:99]
	s_nop 5
	v_lshlrev_b32_e32 v96, 16, v208
	v_and_b32_e32 v97, 0xffff0000, v208
	v_lshlrev_b32_e32 v98, 16, v209
	v_and_b32_e32 v99, 0xffff0000, v209
	v_mfma_f32_16x16x32_bf16 v[100:103], v[230:233], v[116:119], v[100:103]
	v_lshlrev_b32_e32 v116, 16, v202
	v_and_b32_e32 v117, 0xffff0000, v202
	v_lshlrev_b32_e32 v118, 16, v203
	v_and_b32_e32 v119, 0xffff0000, v203
	v_mfma_f32_16x16x32_bf16 v[96:99], v[108:111], v[132:135], v[96:99]
	v_mfma_f32_16x16x32_bf16 v[104:107], v[108:111], v[140:143], v[104:107]
	v_mfma_f32_16x16x32_bf16 v[108:111], v[108:111], v[112:115], v[116:119]
	v_mfma_f32_16x16x32_bf16 v[96:99], v[222:225], v[132:135], v[96:99]
	v_mfma_f32_16x16x32_bf16 v[104:107], v[222:225], v[140:143], v[104:107]
	v_mfma_f32_16x16x32_bf16 v[108:111], v[222:225], v[112:115], v[108:111]
	v_lshl_add_u64 v[114:115], v[176:177], 0, v[186:187]
	v_add_co_u32_e32 v116, vcc, s11, v114
	v_mfma_f32_16x16x32_bf16 v[96:99], v[226:229], v[128:131], v[96:99]
	s_nop 0
	v_addc_co_u32_e32 v117, vcc, 0, v115, vcc
	v_cvt_pk_bf16_f32 v112, v152, v153
	v_mfma_f32_16x16x32_bf16 v[104:107], v[226:229], v[120:123], v[104:107]
	v_cvt_pk_bf16_f32 v113, v154, v155
	v_add_co_u32_e32 v114, vcc, s12, v114
	v_mfma_f32_16x16x32_bf16 v[108:111], v[226:229], v[136:139], v[108:111]
	global_store_dwordx2 v[116:117], v[112:113], off
	v_cvt_pk_bf16_f32 v112, v144, v145
	v_cvt_pk_bf16_f32 v113, v146, v147
	v_mfma_f32_16x16x32_bf16 v[96:99], v[230:233], v[128:131], v[96:99]
	v_addc_co_u32_e32 v115, vcc, 0, v115, vcc
	global_store_dwordx2 v[114:115], v[112:113], off
	v_mfma_f32_16x16x32_bf16 v[104:107], v[230:233], v[120:123], v[104:107]
	v_mfma_f32_16x16x32_bf16 v[108:111], v[230:233], v[136:139], v[108:111]
	s_branch .LBB0_836
.LBB0_839:
	v_readlane_b32 s4, v242, 1
	v_readlane_b32 s5, v242, 2
	s_mov_b64 s[0:1], s[4:5]
	s_waitcnt vmcnt(0)
	v_lshlrev_b32_e32 v1, 4, v218
	s_add_u32 s0, s0, s3
	v_lshlrev_b32_e32 v0, 10, v214
	v_and_b32_e32 v1, 0x300, v1
	s_addc_u32 s1, s1, 0
	v_or3_b32 v0, v0, v1, v215
	s_add_u32 s0, s0, 0x420e000
	v_lshlrev_b32_e32 v0, 2, v0
	s_addc_u32 s1, s1, 0
	v_or_b32_e32 v1, 64, v0
	v_readlane_b32 s6, v242, 3
	v_readlane_b32 s7, v242, 4
	v_readlane_b32 s8, v242, 5
	v_readlane_b32 s9, v242, 6
	v_readlane_b32 s10, v242, 7
	v_readlane_b32 s11, v242, 8
	global_store_dword v0, v96, s[0:1]
	global_store_dword v0, v97, s[0:1] offset:256
	global_store_dword v0, v98, s[0:1] offset:512
	global_store_dword v0, v99, s[0:1] offset:768
	global_store_dword v0, v100, s[0:1] offset:64
	global_store_dword v1, v101, s[0:1] offset:256
	global_store_dword v1, v102, s[0:1] offset:512
	global_store_dword v1, v103, s[0:1] offset:768
	global_store_dword v0, v104, s[0:1] offset:128
	v_or_b32_e32 v1, 0x80, v0
	v_readlane_b32 s12, v242, 9
	v_readlane_b32 s13, v242, 10
	v_readlane_b32 s14, v242, 11
	v_readlane_b32 s15, v242, 12
	s_mov_b64 s[4:5], s[8:9]
	global_store_dword v1, v105, s[0:1] offset:256
	global_store_dword v1, v106, s[0:1] offset:512
	global_store_dword v1, v107, s[0:1] offset:768
	global_store_dword v0, v108, s[0:1] offset:192
	v_or_b32_e32 v0, 0xc0, v0
	v_readlane_b32 s16, v242, 13
	v_readlane_b32 s17, v242, 14
	v_readlane_b32 s18, v242, 15
	v_readlane_b32 s19, v242, 16
	s_mov_b64 s[6:7], s[10:11]
	s_mov_b64 s[8:9], s[12:13]
	s_mov_b64 s[10:11], s[14:15]
	global_store_dword v0, v109, s[0:1] offset:256
	global_store_dword v0, v110, s[0:1] offset:512
	global_store_dword v0, v111, s[0:1] offset:768
	s_cmp_lt_i32 s93, 7
	s_cbranch_scc1 .LBB0_893
